# loop-edge: MLA and DIFF tile-loop back edges rotated so the per-tile barrier sits at the loop head
# baseline (speedup 1.0000x reference)
; template <bool DIFF>
; DI void attn_phase(const AttnArgs& a, char* lds) {
;     ...
; #pragma unroll 1
;     for (int t = t_beg; t < t_end; ++t) {
;     ...
;       __syncthreads();
.Lmla_noprio:
.Lmla_head:
	s_barrier

; template <bool DIFF>
; DI void attn_phase(const AttnArgs& a, char* lds) {
;     ...
; #pragma unroll 1
;     for (int t = t_beg; t < t_end; ++t) {
;     ...
;       __syncthreads();
.LBB0_405:
	s_add_i32 s7, s7, 16
	s_add_i32 s52, s52, 64
	s_addk_i32 s5, 0x2000
	s_cmp_eq_u32 s0, s53
	s_waitcnt vmcnt(0) lgkmcnt(0)
	s_cbranch_scc1 .Lmla_exit
	s_mov_b32 s22, s53
	s_branch .Lmla_head
.Lmla_exit:
	s_barrier
	s_branch .LBB0_370

; DI u32 pk2(float a, float b) { f2_t v = {a, b}; bf2_t r = __builtin_convertvector(v, bf2_t); return __builtin_bit_cast(u32, r); }
; DI float bflo(u32 u) { return __uint_as_float(u << 16); }
; DI float bfhi(u32 u) { return __uint_as_float(u & 0xffff0000u); }
; DI float xor32_sum(float v) { auto rr = __builtin_amdgcn_permlane32_swap(__float_as_uint(v), __float_as_uint(v), false, false); return __uint_as_float(rr[0]) + __uint_as_float(rr[1]); }
; template <bool DIFF>
; DI void attn_phase(const AttnArgs& a, char* lds) {
;     ...
;       if (DIFF) {
;         float ss = 0.f;
; #pragma unroll
;         for (int ds = 0; ds < NDS; ++ds) {
;           const u32x4 w = __builtin_bit_cast(u32x4, qf[ds]);
; #pragma unroll
;           for (int i = 0; i < 4; ++i) { const float x0 = bflo(w[i]), x1 = bfhi(w[i]); ss += x0 * x0 + x1 * x1; }
;         }
;         ss = xor32_sum(ss);
;         const float ri = rsqrtf(ss * (1.0f / 128.0f) + EPS) * QSCALE_B;
; #pragma unroll
;         for (int ds = 0; ds < NDS; ++ds) {
;           const u32x4 w = __builtin_bit_cast(u32x4, qf[ds]);
;           const float4 ga = *(const float4*)(a.qgain + ds * 16 + (tq >> 5) * 8), gb = *(const float4*)(a.qgain + ds * 16 + (tq >> 5) * 8 + 4);
;           u32x4 o4;
;           o4[0] = pk2(bflo(w[0]) * ri * ga.x, bfhi(w[0]) * ri * ga.y); o4[1] = pk2(bflo(w[1]) * ri * ga.z, bfhi(w[1]) * ri * ga.w);
;           o4[2] = pk2(bflo(w[2]) * ri * gb.x, bfhi(w[2]) * ri * gb.y); o4[3] = pk2(bflo(w[3]) * ri * gb.z, bfhi(w[3]) * ri * gb.w);
;           qf[ds] = __builtin_bit_cast(bf16x8, o4);
;         }
.LBB0_597:
	s_andn2_b64 vcc, exec, s[66:67]
	s_waitcnt vmcnt(0) lgkmcnt(0)
	s_barrier
	s_cbranch_vccnz .LBB0_630
	v_add_f32_e32 v0, v136, v87
	v_fmamk_f32 v0, v0, 0x3c000000, v212
	v_mul_f32_e32 v87, 0x4b800000, v0
	v_cmp_gt_f32_e32 vcc, s72, v0
	v_mov_b32_e32 v89, v95
	v_mov_b32_e32 v95, v117
	v_cndmask_b32_e32 v0, v0, v87, vcc
	v_rsq_f32_e32 v0, v0
	v_mov_b32_e32 v87, v97
	v_mov_b32_e32 v97, v119
	v_mov_b32_e32 v91, v93
	v_mul_f32_e32 v116, 0x45800000, v0
	v_cndmask_b32_e32 v0, v0, v116, vcc
	v_mul_f32_e32 v0, 0x3e0293ee, v0
	v_pk_mul_f32 v[116:117], v[0:1], v[134:135] op_sel_hi:[0,1]
	v_pk_mul_f32 v[62:63], v[62:63], v[116:117]
	v_mov_b32_e32 v93, v123
	v_cvt_pk_bf16_f32 v176, v62, v63
	v_pk_mul_f32 v[62:63], v[0:1], v[132:133] op_sel_hi:[0,1]
	v_pk_mul_f32 v[62:63], v[64:65], v[62:63]
	s_add_i32 s4, s0, 1
	v_cvt_pk_bf16_f32 v177, v62, v63
	v_pk_mul_f32 v[62:63], v[0:1], v[130:131] op_sel_hi:[0,1]
	v_pk_mul_f32 v[58:59], v[58:59], v[62:63]
	v_cvt_f32_i32_e32 v221, v138
	v_cvt_pk_bf16_f32 v178, v58, v59
	v_pk_mul_f32 v[58:59], v[0:1], v[128:129] op_sel_hi:[0,1]
	v_pk_mul_f32 v[58:59], v[60:61], v[58:59]
	v_cndmask_b32_e64 v222, 0, 1, s[8:9]
	v_cvt_pk_bf16_f32 v179, v58, v59
	v_pk_mul_f32 v[58:59], v[0:1], v[126:127] op_sel_hi:[0,1]
	v_pk_mul_f32 v[54:55], v[54:55], v[58:59]
	v_cndmask_b32_e64 v225, v215, 0, s[8:9]
	v_cvt_pk_bf16_f32 v180, v54, v55
	v_pk_mul_f32 v[54:55], v[0:1], v[124:125] op_sel_hi:[0,1]
	v_pk_mul_f32 v[54:55], v[56:57], v[54:55]
	v_mov_b32_e32 v226, 0
	v_cvt_pk_bf16_f32 v181, v54, v55
	v_pk_mul_f32 v[54:55], v[0:1], v[120:121] op_sel_hi:[0,1]
	v_pk_mul_f32 v[50:51], v[54:55], v[50:51]
	s_nop 0
	v_cvt_pk_bf16_f32 v182, v50, v51
	v_pk_mul_f32 v[50:51], v[0:1], v[66:67] op_sel_hi:[0,1]
	v_pk_mul_f32 v[50:51], v[50:51], v[52:53]
	s_nop 0
	v_cvt_pk_bf16_f32 v183, v50, v51
	v_pk_mul_f32 v[50:51], v[0:1], v[114:115] op_sel_hi:[0,1]
	v_pk_mul_f32 v[46:47], v[50:51], v[46:47]
	s_nop 0
	v_cvt_pk_bf16_f32 v184, v46, v47
	v_pk_mul_f32 v[46:47], v[0:1], v[68:69] op_sel_hi:[0,1]
	v_pk_mul_f32 v[46:47], v[46:47], v[48:49]
	s_nop 0
	v_cvt_pk_bf16_f32 v185, v46, v47
	v_pk_mul_f32 v[46:47], v[0:1], v[112:113] op_sel_hi:[0,1]
	v_pk_mul_f32 v[42:43], v[46:47], v[42:43]
	s_nop 0
	v_cvt_pk_bf16_f32 v186, v42, v43
	v_pk_mul_f32 v[42:43], v[0:1], v[70:71] op_sel_hi:[0,1]
	v_pk_mul_f32 v[42:43], v[42:43], v[44:45]
	s_nop 0
	v_cvt_pk_bf16_f32 v187, v42, v43
	v_pk_mul_f32 v[42:43], v[0:1], v[110:111] op_sel_hi:[0,1]
	v_pk_mul_f32 v[38:39], v[42:43], v[38:39]
	s_nop 0
	v_cvt_pk_bf16_f32 v188, v38, v39
	v_pk_mul_f32 v[38:39], v[0:1], v[72:73] op_sel_hi:[0,1]
	v_pk_mul_f32 v[38:39], v[38:39], v[40:41]
	s_nop 0
	v_cvt_pk_bf16_f32 v189, v38, v39
	v_pk_mul_f32 v[38:39], v[0:1], v[108:109] op_sel_hi:[0,1]
	v_pk_mul_f32 v[34:35], v[38:39], v[34:35]
	s_nop 0
	v_cvt_pk_bf16_f32 v190, v34, v35
	v_pk_mul_f32 v[34:35], v[0:1], v[74:75] op_sel_hi:[0,1]
	v_pk_mul_f32 v[34:35], v[34:35], v[36:37]
	s_nop 0
	v_cvt_pk_bf16_f32 v191, v34, v35
	v_pk_mul_f32 v[34:35], v[0:1], v[106:107] op_sel_hi:[0,1]
	v_pk_mul_f32 v[30:31], v[34:35], v[30:31]
	s_nop 0
	v_cvt_pk_bf16_f32 v192, v30, v31
	v_pk_mul_f32 v[30:31], v[0:1], v[76:77] op_sel_hi:[0,1]
	v_pk_mul_f32 v[30:31], v[30:31], v[32:33]
	s_nop 0
	v_cvt_pk_bf16_f32 v193, v30, v31
	v_pk_mul_f32 v[30:31], v[0:1], v[104:105] op_sel_hi:[0,1]
	v_pk_mul_f32 v[26:27], v[30:31], v[26:27]
	s_nop 0
	v_cvt_pk_bf16_f32 v194, v26, v27
	v_pk_mul_f32 v[26:27], v[0:1], v[78:79] op_sel_hi:[0,1]
	v_pk_mul_f32 v[26:27], v[26:27], v[28:29]
	s_nop 0
	v_cvt_pk_bf16_f32 v195, v26, v27
	v_pk_mul_f32 v[26:27], v[0:1], v[102:103] op_sel_hi:[0,1]
	v_pk_mul_f32 v[22:23], v[26:27], v[22:23]
	s_nop 0
	v_cvt_pk_bf16_f32 v196, v22, v23
	v_pk_mul_f32 v[22:23], v[0:1], v[80:81] op_sel_hi:[0,1]
	v_pk_mul_f32 v[22:23], v[22:23], v[24:25]
	s_nop 0
	v_cvt_pk_bf16_f32 v197, v22, v23
	v_pk_mul_f32 v[22:23], v[0:1], v[100:101] op_sel_hi:[0,1]
	v_pk_mul_f32 v[18:19], v[22:23], v[18:19]
	s_nop 0
	v_cvt_pk_bf16_f32 v198, v18, v19
	v_pk_mul_f32 v[18:19], v[0:1], v[82:83] op_sel_hi:[0,1]
	v_pk_mul_f32 v[18:19], v[18:19], v[20:21]
	s_nop 0
	v_cvt_pk_bf16_f32 v199, v18, v19
	v_pk_mul_f32 v[18:19], v[0:1], v[98:99] op_sel_hi:[0,1]
	v_pk_mul_f32 v[14:15], v[18:19], v[14:15]
	s_nop 0
	v_cvt_pk_bf16_f32 v200, v14, v15
	v_pk_mul_f32 v[14:15], v[0:1], v[84:85] op_sel_hi:[0,1]
	v_pk_mul_f32 v[14:15], v[14:15], v[16:17]
	s_nop 0
	v_cvt_pk_bf16_f32 v201, v14, v15
	v_pk_mul_f32 v[14:15], v[0:1], v[96:97] op_sel_hi:[0,1]
	v_pk_mul_f32 v[10:11], v[14:15], v[10:11]
	v_mov_b32_e32 v14, v1
	v_cvt_pk_bf16_f32 v202, v10, v11
	v_pk_mul_f32 v[10:11], v[0:1], v[86:87] op_sel_hi:[0,1]
	v_pk_mul_f32 v[10:11], v[10:11], v[12:13]
	v_mov_b32_e32 v15, v1
	v_cvt_pk_bf16_f32 v203, v10, v11
	v_pk_mul_f32 v[10:11], v[0:1], v[94:95] op_sel_hi:[0,1]
	v_pk_mul_f32 v[6:7], v[10:11], v[6:7]
; template <bool DIFF>
; DI void attn_phase(const AttnArgs& a, char* lds) {
;     ...
;         for (int ds = 0; ds < NDS; ++ds) {
;           const u32x4 w = __builtin_bit_cast(u32x4, qf[ds]);
;           const float4 ga = *(const float4*)(a.qgain + ds * 16 + (tq >> 5) * 8), gb = *(const float4*)(a.qgain + ds * 16 + (tq >> 5) * 8 + 4);
;           u32x4 o4;
;           o4[0] = pk2(bflo(w[0]) * ri * ga.x, bfhi(w[0]) * ri * ga.y); o4[1] = pk2(bflo(w[1]) * ri * ga.z, bfhi(w[1]) * ri * ga.w);
;           o4[2] = pk2(bflo(w[2]) * ri * gb.x, bfhi(w[2]) * ri * gb.y); o4[3] = pk2(bflo(w[3]) * ri * gb.z, bfhi(w[3]) * ri * gb.w);
;           qf[ds] = __builtin_bit_cast(bf16x8, o4);
;         }
;       }
;     }
;     const int g32 = __builtin_amdgcn_readfirstlane((qb * QROWS + rg * 32) >> 5);
;     const int wqcmin = c32[g32], wqcmax = c32[512 + g32];
;     int t_end = c32[C_TEND + qb * (QROWS / 32)];
; #pragma unroll
;     for (int i = 1; i < QROWS / 32; ++i) t_end = max(t_end, c32[C_TEND + qb * (QROWS / 32) + i]);
;     t_end = __builtin_amdgcn_readfirstlane(t_end);
;     int t_beg = 0;
;     int wpmin = 0, wpmax = 0;
;     float lim2 = 0.f;
;     if (DIFF) {
;       t_beg = c32[C_TBEG + h * 512 + qb * 4];
; #pragma unroll
;       for (int i = 1; i < 4; ++i) t_beg = min(t_beg, c32[C_TBEG + h * 512 + qb * 4 + i]);
;       t_beg = __builtin_amdgcn_readfirstlane(t_beg);
;       wpmin = c32[C_PMIN + g32]; wpmax = c32[C_PMAX + g32];
;       lim2 = a.lamtab[2];
;     }
;     const float slope2 = DIFF ? exp2f(-(float)(h + 1)) * LOG2E : 0.f;
;     ...
;     f32x16 o[NM];
; #pragma unroll
;     for (int m = 0; m < NM; ++m)
; #pragma unroll
;       for (int r = 0; r < 16; ++r) o[m][r] = 0.f;
;     const float sbound = a.lamtab_all[DIFF ? 4 : 3];
;     const int usefix_i = __builtin_amdgcn_readfirstlane(sbound < 40.0f ? 1 : 0);
;     const bool usefix = usefix_i != 0;
;     float m_ref = usefix ? 0.f : -1e30f, l_sum = 0.f;
;     f32x16 negm;
; #pragma unroll
;     for (int r = 0; r < 16; ++r) negm[r] = 0.f;
;     ...
;     for (int t = t_beg; t < t_end; ++t) {
;       const char* sb = lds + (t & 1) * STAGE;
;       char* nb = lds + ((t + 1) & 1) * STAGE;
;       const bool nxt = t + 1 < t_end;
;       const int4 tinfo = *(const int4*)(ttab + 4 * t);
;       const int kcmin = __builtin_amdgcn_readfirstlane(tinfo.x), kcmax = __builtin_amdgcn_readfirstlane(tinfo.y);
;       bool skip = kcmin > wqcmax;
	v_mov_b32_e32 v10, v1
	v_cvt_pk_bf16_f32 v204, v6, v7
	v_pk_mul_f32 v[6:7], v[0:1], v[88:89] op_sel_hi:[0,1]
	v_pk_mul_f32 v[6:7], v[6:7], v[8:9]
	v_mov_b32_e32 v8, v1
	v_cvt_pk_bf16_f32 v205, v6, v7
	v_pk_mul_f32 v[6:7], v[0:1], v[92:93] op_sel_hi:[0,1]
	v_pk_mul_f32 v[2:3], v[6:7], v[2:3]
	v_cvt_f32_i32_e32 v6, s4
	v_cvt_pk_bf16_f32 v206, v2, v3
	v_pk_mul_f32 v[2:3], v[0:1], v[90:91] op_sel_hi:[0,1]
	v_pk_mul_f32 v[2:3], v[2:3], v[4:5]
	v_cmp_lt_f32_e32 vcc, s73, v6
	s_and_b64 s[4:5], vcc, exec
	s_cselect_b32 s4, 0xffffffc0, 0
	v_cndmask_b32_e32 v0, 0, v214, vcc
	v_sub_f32_e32 v0, v0, v6
	v_exp_f32_e32 v0, v0
	s_lshl_b32 s0, s0, 22
	v_cvt_pk_bf16_f32 v207, v2, v3
	v_mov_b32_e32 v2, v1
	v_ldexp_f32 v0, v0, s4
	v_mul_f32_e32 v223, 0x3fb8aa3b, v0
	v_cvt_i32_f32_e32 v0, v221
	s_lshl_b32 s4, s1, 4
	s_add_i32 s80, s4, 0x20ff0
	s_lshl_b32 s4, s1, 6
	s_add_i32 s81, s4, 64
	s_lshl_b32 s4, s1, 14
	v_ashrrev_i32_e32 v224, 6, v0
	s_add_i32 s0, s0, s4
	v_mov_b32_e32 v0, v1
	v_mov_b32_e32 v3, v1
	v_mov_b32_e32 v4, v1
	v_mov_b32_e32 v5, v1
	v_mov_b32_e32 v6, v1
	v_mov_b32_e32 v7, v1
	v_mov_b32_e32 v9, v1
	v_mov_b32_e32 v11, v1
	v_mov_b32_e32 v12, v1
	v_mov_b32_e32 v13, v1
	v_mov_b64_e32 v[30:31], v[14:15]
	v_mov_b64_e32 v[46:47], v[14:15]
	v_mov_b64_e32 v[62:63], v[14:15]
	v_mov_b64_e32 v[78:79], v[14:15]
	v_mov_b64_e32 v[94:95], v[14:15]
	v_mov_b64_e32 v[110:111], v[14:15]
	v_mov_b64_e32 v[126:127], v[14:15]
	v_mov_b64_e32 v[142:143], v[14:15]
	s_add_i32 s79, s75, 0x800
	s_add_i32 s82, s0, 0x4000
	v_mov_b64_e32 v[28:29], v[12:13]
	v_mov_b64_e32 v[26:27], v[10:11]
	v_mov_b64_e32 v[24:25], v[8:9]
	v_mov_b64_e32 v[22:23], v[6:7]
	v_mov_b64_e32 v[20:21], v[4:5]
	v_mov_b64_e32 v[18:19], v[2:3]
	v_mov_b64_e32 v[16:17], v[0:1]
	v_mov_b64_e32 v[44:45], v[12:13]
	v_mov_b64_e32 v[42:43], v[10:11]
	v_mov_b64_e32 v[40:41], v[8:9]
	v_mov_b64_e32 v[38:39], v[6:7]
	v_mov_b64_e32 v[36:37], v[4:5]
	v_mov_b64_e32 v[34:35], v[2:3]
	v_mov_b64_e32 v[32:33], v[0:1]
	v_mov_b64_e32 v[60:61], v[12:13]
	v_mov_b64_e32 v[58:59], v[10:11]
	v_mov_b64_e32 v[56:57], v[8:9]
	v_mov_b64_e32 v[54:55], v[6:7]
	v_mov_b64_e32 v[52:53], v[4:5]
	v_mov_b64_e32 v[50:51], v[2:3]
	v_mov_b64_e32 v[48:49], v[0:1]
	v_mov_b64_e32 v[76:77], v[12:13]
	v_mov_b64_e32 v[74:75], v[10:11]
	v_mov_b64_e32 v[72:73], v[8:9]
	v_mov_b64_e32 v[70:71], v[6:7]
	v_mov_b64_e32 v[68:69], v[4:5]
	v_mov_b64_e32 v[66:67], v[2:3]
	v_mov_b64_e32 v[64:65], v[0:1]
	v_mov_b64_e32 v[92:93], v[12:13]
	v_mov_b64_e32 v[90:91], v[10:11]
	v_mov_b64_e32 v[88:89], v[8:9]
	v_mov_b64_e32 v[86:87], v[6:7]
	v_mov_b64_e32 v[84:85], v[4:5]
	v_mov_b64_e32 v[82:83], v[2:3]
	v_mov_b64_e32 v[80:81], v[0:1]
	v_mov_b64_e32 v[108:109], v[12:13]
	v_mov_b64_e32 v[106:107], v[10:11]
	v_mov_b64_e32 v[104:105], v[8:9]
	v_mov_b64_e32 v[102:103], v[6:7]
	v_mov_b64_e32 v[100:101], v[4:5]
	v_mov_b64_e32 v[98:99], v[2:3]
	v_mov_b64_e32 v[96:97], v[0:1]
	v_mov_b64_e32 v[124:125], v[12:13]
	v_mov_b64_e32 v[122:123], v[10:11]
	v_mov_b64_e32 v[120:121], v[8:9]
	v_mov_b64_e32 v[118:119], v[6:7]
	v_mov_b64_e32 v[116:117], v[4:5]
	v_mov_b64_e32 v[114:115], v[2:3]
	v_mov_b64_e32 v[112:113], v[0:1]
	v_mov_b64_e32 v[140:141], v[12:13]
	v_mov_b64_e32 v[138:139], v[10:11]
	v_mov_b64_e32 v[136:137], v[8:9]
	v_mov_b64_e32 v[134:135], v[6:7]
	v_mov_b64_e32 v[132:133], v[4:5]
	v_mov_b64_e32 v[130:131], v[2:3]
	v_mov_b64_e32 v[128:129], v[0:1]
.Ldiff_head:
	s_barrier
.LBB0_599:
	v_mov_b32_e32 v0, s80
	ds_read_b128 v[2:5], v0
	s_add_i32 s83, s1, 1
	s_cmp_ge_i32 s83, s78
	s_cselect_b64 s[66:67], -1, 0
	s_bitcmp1_b32 s83, 0
	s_cselect_b32 s85, 0x10200, 0
	s_add_i32 s86, s85, s33
	s_waitcnt lgkmcnt(0)
	v_readfirstlane_b32 s0, v2
	v_readfirstlane_b32 s4, v3
	v_readfirstlane_b32 s5, v4
	v_readfirstlane_b32 s8, v5
	s_nop 1
	v_subrev_u32_e32 v0, s8, v219
	v_sub_u32_e32 v2, s5, v217
	v_max3_i32 v0, v0, v2, 0
	v_cvt_f32_u32_e32 v0, v0
	s_bitcmp1_b32 s1, 0
	s_cselect_b32 s84, 0x10200, 0
	s_cmp_gt_i32 s0, s77
	v_mul_f32_e32 v0, v223, v0
	s_cselect_b64 s[0:1], -1, 0
	v_cmp_gt_f32_e32 vcc, v0, v218
	v_mov_b32_e32 v0, v222
	s_or_b64 s[68:69], s[0:1], vcc
	s_nop 0
	v_readfirstlane_b32 s0, v0
	s_cmp_eq_u32 s0, 0
	s_cselect_b64 s[8:9], -1, 0
	s_or_b64 s[8:9], s[8:9], s[68:69]
	s_and_b64 vcc, exec, s[8:9]
	v_cmp_gt_i32_e64 s[8:9], s4, v220
	s_nop 1
	v_cndmask_b32_e64 v0, 0, 1, s[8:9]
	v_cmp_ne_u32_e64 s[8:9], 1, v0
	s_cbranch_vccnz .Ldiff_slow
	s_or_b64 vcc, s[66:67], s[6:7]
	s_and_b64 vcc, exec, vcc
	s_cbranch_vccnz .Ldiff_nw0
	v_and_b32_e32 v0, 63, v208
	v_add_u32_e32 v2, s81, v0
	v_ashrrev_i32_e32 v3, 31, v2
	v_lshlrev_b64 v[2:3], 2, v[2:3]
	v_lshl_add_u64 v[4:5], s[48:49], 0, v[2:3]
	s_add_i32 m0, s85, 0x10000
	v_lshl_add_u64 v[2:3], s[38:39], 0, v[2:3]
	global_load_lds_dword v[2:3], off
	s_add_i32 m0, s85, 0x10100
	s_nop 0
	global_load_lds_dword v[4:5], off

; template <bool DIFF>
; DI void attn_phase(const AttnArgs& a, char* lds) {
;     ...
; #pragma unroll 1
;     for (int t = t_beg; t < t_end; ++t) {
;     ...
;       __syncthreads();
.LBB0_628:
	s_add_i32 s80, s80, 16
	s_add_i32 s81, s81, 64
	s_addk_i32 s82, 0x4000
	s_and_b64 vcc, exec, s[66:67]
	s_waitcnt vmcnt(0) lgkmcnt(0)
	s_cbranch_vccnz .Ldiff_exit
	s_mov_b32 s1, s83
	s_branch .Ldiff_head
